# ygemm epilogue: packed f32 gelu and scalar-base store addressing
# speedup vs baseline: 1.0088x; 1.0088x over previous
.LBB0_596:
	s_lshl_b32 s20, s42, 5
	s_lshl_b32 s21, s67, 24
	s_add_i32 s20, s20, s21
	s_add_i32 s20, s20, 0xa000000
	s_add_u32 s44, s34, s20
	s_addc_u32 s45, s35, 0
	v_and_b32_e32 v145, 15, v181
	v_lshlrev_b32_e32 v145, 1, v145
	v_lshl_add_u32 v145, v144, 16, v145
	v_add_u32_e32 v145, v145, v132
	v_mov_b32_e32 v156, 0xc0135761
	v_mov_b32_e32 v157, 0xc0135761
	v_mov_b32_e32 v158, 0xbdd2d3e7
	v_mov_b32_e32 v159, 0xbdd2d3e7
	v_mov_b32_e32 v160, 0x3f800000
	v_mov_b32_e32 v161, 0x3f800000
	v_pk_mul_f32 v[146:147], v[124:125], v[124:125]
	v_pk_mul_f32 v[148:149], v[126:127], v[126:127]
	v_pk_fma_f32 v[146:147], v[146:147], v[158:159], v[156:157]
	v_pk_fma_f32 v[148:149], v[148:149], v[158:159], v[156:157]
	v_pk_mul_f32 v[146:147], v[124:125], v[146:147]
	v_pk_mul_f32 v[148:149], v[126:127], v[148:149]
	v_exp_f32_e32 v146, v146
	v_exp_f32_e32 v147, v147
	v_exp_f32_e32 v148, v148
	v_exp_f32_e32 v149, v149
	v_pk_add_f32 v[146:147], v[146:147], v[160:161]
	v_pk_add_f32 v[148:149], v[148:149], v[160:161]
	v_rcp_f32_e32 v146, v146
	v_rcp_f32_e32 v147, v147
	v_rcp_f32_e32 v148, v148
	v_rcp_f32_e32 v149, v149
	v_pk_mul_f32 v[146:147], v[124:125], v[146:147]
	v_pk_mul_f32 v[148:149], v[126:127], v[148:149]
	v_cvt_pk_bf16_f32 v154, v146, v147
	v_cvt_pk_bf16_f32 v155, v148, v149
	global_store_short v145, v154, s[44:45]
	s_add_u32 s46, s44, 0x10000
	s_addc_u32 s47, s45, 0
	global_store_short_d16_hi v145, v154, s[46:47]
	s_add_u32 s46, s44, 0x20000
	s_addc_u32 s47, s45, 0
	global_store_short v145, v155, s[46:47]
	s_add_u32 s46, s44, 0x30000
	s_addc_u32 s47, s45, 0
	global_store_short_d16_hi v145, v155, s[46:47]
	v_pk_mul_f32 v[146:147], v[120:121], v[120:121]
	v_pk_mul_f32 v[148:149], v[122:123], v[122:123]
	v_pk_fma_f32 v[146:147], v[146:147], v[158:159], v[156:157]
	v_pk_fma_f32 v[148:149], v[148:149], v[158:159], v[156:157]
	v_pk_mul_f32 v[146:147], v[120:121], v[146:147]
	v_pk_mul_f32 v[148:149], v[122:123], v[148:149]
	v_exp_f32_e32 v146, v146
	v_exp_f32_e32 v147, v147
	v_exp_f32_e32 v148, v148
	v_exp_f32_e32 v149, v149
	v_pk_add_f32 v[146:147], v[146:147], v[160:161]
	v_pk_add_f32 v[148:149], v[148:149], v[160:161]
	v_rcp_f32_e32 v146, v146
	v_rcp_f32_e32 v147, v147
	v_rcp_f32_e32 v148, v148
	v_rcp_f32_e32 v149, v149
	v_pk_mul_f32 v[146:147], v[120:121], v[146:147]
	v_pk_mul_f32 v[148:149], v[122:123], v[148:149]
	v_cvt_pk_bf16_f32 v154, v146, v147
	v_cvt_pk_bf16_f32 v155, v148, v149
	s_add_u32 s46, s44, 0x1000
	s_addc_u32 s47, s45, 0
	global_store_short v145, v154, s[46:47]
	s_add_u32 s46, s44, 0x11000
	s_addc_u32 s47, s45, 0
	global_store_short_d16_hi v145, v154, s[46:47]
	s_add_u32 s46, s44, 0x21000
	s_addc_u32 s47, s45, 0
	global_store_short v145, v155, s[46:47]
	s_add_u32 s46, s44, 0x31000
	s_addc_u32 s47, s45, 0
	global_store_short_d16_hi v145, v155, s[46:47]
	v_pk_mul_f32 v[146:147], v[116:117], v[116:117]
	v_pk_mul_f32 v[148:149], v[118:119], v[118:119]
	v_pk_fma_f32 v[146:147], v[146:147], v[158:159], v[156:157]
	v_pk_fma_f32 v[148:149], v[148:149], v[158:159], v[156:157]
	v_pk_mul_f32 v[146:147], v[116:117], v[146:147]
	v_pk_mul_f32 v[148:149], v[118:119], v[148:149]
	v_exp_f32_e32 v146, v146
	v_exp_f32_e32 v147, v147
	v_exp_f32_e32 v148, v148
	v_exp_f32_e32 v149, v149
	v_pk_add_f32 v[146:147], v[146:147], v[160:161]
	v_pk_add_f32 v[148:149], v[148:149], v[160:161]
	v_rcp_f32_e32 v146, v146
	v_rcp_f32_e32 v147, v147
	v_rcp_f32_e32 v148, v148
	v_rcp_f32_e32 v149, v149
	v_pk_mul_f32 v[146:147], v[116:117], v[146:147]
	v_pk_mul_f32 v[148:149], v[118:119], v[148:149]
	v_cvt_pk_bf16_f32 v154, v146, v147
	v_cvt_pk_bf16_f32 v155, v148, v149
	s_add_u32 s46, s44, 0x2000
	s_addc_u32 s47, s45, 0
	global_store_short v145, v154, s[46:47]
	s_add_u32 s46, s44, 0x12000
	s_addc_u32 s47, s45, 0
	global_store_short_d16_hi v145, v154, s[46:47]
	s_add_u32 s46, s44, 0x22000
	s_addc_u32 s47, s45, 0
	global_store_short v145, v155, s[46:47]
	s_add_u32 s46, s44, 0x32000
	s_addc_u32 s47, s45, 0
	global_store_short_d16_hi v145, v155, s[46:47]
	v_pk_mul_f32 v[146:147], v[112:113], v[112:113]
	v_pk_mul_f32 v[148:149], v[114:115], v[114:115]
	v_pk_fma_f32 v[146:147], v[146:147], v[158:159], v[156:157]
	v_pk_fma_f32 v[148:149], v[148:149], v[158:159], v[156:157]
	v_pk_mul_f32 v[146:147], v[112:113], v[146:147]
	v_pk_mul_f32 v[148:149], v[114:115], v[148:149]
	v_exp_f32_e32 v146, v146
	v_exp_f32_e32 v147, v147
	v_exp_f32_e32 v148, v148
	v_exp_f32_e32 v149, v149
	v_pk_add_f32 v[146:147], v[146:147], v[160:161]
	v_pk_add_f32 v[148:149], v[148:149], v[160:161]
	v_rcp_f32_e32 v146, v146
	v_rcp_f32_e32 v147, v147
	v_rcp_f32_e32 v148, v148
	v_rcp_f32_e32 v149, v149
	v_pk_mul_f32 v[146:147], v[112:113], v[146:147]
	v_pk_mul_f32 v[148:149], v[114:115], v[148:149]
	v_cvt_pk_bf16_f32 v154, v146, v147
	v_cvt_pk_bf16_f32 v155, v148, v149
	s_add_u32 s46, s44, 0x3000
	s_addc_u32 s47, s45, 0
	global_store_short v145, v154, s[46:47]
	s_add_u32 s46, s44, 0x13000
	s_addc_u32 s47, s45, 0
	global_store_short_d16_hi v145, v154, s[46:47]
	s_add_u32 s46, s44, 0x23000
	s_addc_u32 s47, s45, 0
	global_store_short v145, v155, s[46:47]
	s_add_u32 s46, s44, 0x33000
	s_addc_u32 s47, s45, 0
	global_store_short_d16_hi v145, v155, s[46:47]
	v_pk_mul_f32 v[146:147], v[108:109], v[108:109]
	v_pk_mul_f32 v[148:149], v[110:111], v[110:111]
	v_pk_fma_f32 v[146:147], v[146:147], v[158:159], v[156:157]
	v_pk_fma_f32 v[148:149], v[148:149], v[158:159], v[156:157]
	v_pk_mul_f32 v[146:147], v[108:109], v[146:147]
	v_pk_mul_f32 v[148:149], v[110:111], v[148:149]
	v_exp_f32_e32 v146, v146
	v_exp_f32_e32 v147, v147
	v_exp_f32_e32 v148, v148
	v_exp_f32_e32 v149, v149
	v_pk_add_f32 v[146:147], v[146:147], v[160:161]
	v_pk_add_f32 v[148:149], v[148:149], v[160:161]
	v_rcp_f32_e32 v146, v146
	v_rcp_f32_e32 v147, v147
	v_rcp_f32_e32 v148, v148
	v_rcp_f32_e32 v149, v149
	v_pk_mul_f32 v[146:147], v[108:109], v[146:147]
	v_pk_mul_f32 v[148:149], v[110:111], v[148:149]
	v_cvt_pk_bf16_f32 v154, v146, v147
	v_cvt_pk_bf16_f32 v155, v148, v149
	s_add_u32 s46, s44, 0x100000
	s_addc_u32 s47, s45, 0
	global_store_short v145, v154, s[46:47]
	s_add_u32 s46, s44, 0x110000
	s_addc_u32 s47, s45, 0
	global_store_short_d16_hi v145, v154, s[46:47]
	s_add_u32 s46, s44, 0x120000
	s_addc_u32 s47, s45, 0
	global_store_short v145, v155, s[46:47]
	s_add_u32 s46, s44, 0x130000
	s_addc_u32 s47, s45, 0
	global_store_short_d16_hi v145, v155, s[46:47]
	v_pk_mul_f32 v[146:147], v[104:105], v[104:105]
	v_pk_mul_f32 v[148:149], v[106:107], v[106:107]
	v_pk_fma_f32 v[146:147], v[146:147], v[158:159], v[156:157]
	v_pk_fma_f32 v[148:149], v[148:149], v[158:159], v[156:157]
	v_pk_mul_f32 v[146:147], v[104:105], v[146:147]
	v_pk_mul_f32 v[148:149], v[106:107], v[148:149]
	v_exp_f32_e32 v146, v146
	v_exp_f32_e32 v147, v147
	v_exp_f32_e32 v148, v148
	v_exp_f32_e32 v149, v149
	v_pk_add_f32 v[146:147], v[146:147], v[160:161]
	v_pk_add_f32 v[148:149], v[148:149], v[160:161]
	v_rcp_f32_e32 v146, v146
	v_rcp_f32_e32 v147, v147
	v_rcp_f32_e32 v148, v148
	v_rcp_f32_e32 v149, v149
	v_pk_mul_f32 v[146:147], v[104:105], v[146:147]
	v_pk_mul_f32 v[148:149], v[106:107], v[148:149]
	v_cvt_pk_bf16_f32 v154, v146, v147
	v_cvt_pk_bf16_f32 v155, v148, v149
	s_add_u32 s46, s44, 0x101000
	s_addc_u32 s47, s45, 0
	global_store_short v145, v154, s[46:47]
	s_add_u32 s46, s44, 0x111000
	s_addc_u32 s47, s45, 0
	global_store_short_d16_hi v145, v154, s[46:47]
	s_add_u32 s46, s44, 0x121000
	s_addc_u32 s47, s45, 0
	global_store_short v145, v155, s[46:47]
	s_add_u32 s46, s44, 0x131000
	s_addc_u32 s47, s45, 0
	global_store_short_d16_hi v145, v155, s[46:47]
	v_pk_mul_f32 v[146:147], v[100:101], v[100:101]
	v_pk_mul_f32 v[148:149], v[102:103], v[102:103]
	v_pk_fma_f32 v[146:147], v[146:147], v[158:159], v[156:157]
	v_pk_fma_f32 v[148:149], v[148:149], v[158:159], v[156:157]
	v_pk_mul_f32 v[146:147], v[100:101], v[146:147]
	v_pk_mul_f32 v[148:149], v[102:103], v[148:149]
	v_exp_f32_e32 v146, v146
	v_exp_f32_e32 v147, v147
	v_exp_f32_e32 v148, v148
	v_exp_f32_e32 v149, v149
	v_pk_add_f32 v[146:147], v[146:147], v[160:161]
	v_pk_add_f32 v[148:149], v[148:149], v[160:161]
	v_rcp_f32_e32 v146, v146
	v_rcp_f32_e32 v147, v147
	v_rcp_f32_e32 v148, v148
	v_rcp_f32_e32 v149, v149
	v_pk_mul_f32 v[146:147], v[100:101], v[146:147]
	v_pk_mul_f32 v[148:149], v[102:103], v[148:149]
	v_cvt_pk_bf16_f32 v154, v146, v147
	v_cvt_pk_bf16_f32 v155, v148, v149
	s_add_u32 s46, s44, 0x102000
	s_addc_u32 s47, s45, 0
	global_store_short v145, v154, s[46:47]
	s_add_u32 s46, s44, 0x112000
	s_addc_u32 s47, s45, 0
	global_store_short_d16_hi v145, v154, s[46:47]
	s_add_u32 s46, s44, 0x122000
	s_addc_u32 s47, s45, 0
	global_store_short v145, v155, s[46:47]
	s_add_u32 s46, s44, 0x132000
	s_addc_u32 s47, s45, 0
	global_store_short_d16_hi v145, v155, s[46:47]
	v_pk_mul_f32 v[146:147], v[96:97], v[96:97]
	v_pk_mul_f32 v[148:149], v[98:99], v[98:99]
	v_pk_fma_f32 v[146:147], v[146:147], v[158:159], v[156:157]
	v_pk_fma_f32 v[148:149], v[148:149], v[158:159], v[156:157]
	v_pk_mul_f32 v[146:147], v[96:97], v[146:147]
	v_pk_mul_f32 v[148:149], v[98:99], v[148:149]
	v_exp_f32_e32 v146, v146
	v_exp_f32_e32 v147, v147
	v_exp_f32_e32 v148, v148
	v_exp_f32_e32 v149, v149
	v_pk_add_f32 v[146:147], v[146:147], v[160:161]
	v_pk_add_f32 v[148:149], v[148:149], v[160:161]
	v_rcp_f32_e32 v146, v146
	v_rcp_f32_e32 v147, v147
	v_rcp_f32_e32 v148, v148
	v_rcp_f32_e32 v149, v149
	v_pk_mul_f32 v[146:147], v[96:97], v[146:147]
	v_pk_mul_f32 v[148:149], v[98:99], v[148:149]
	v_cvt_pk_bf16_f32 v154, v146, v147
	v_cvt_pk_bf16_f32 v155, v148, v149
	s_add_u32 s46, s44, 0x103000
	s_addc_u32 s47, s45, 0
	global_store_short v145, v154, s[46:47]
	s_add_u32 s46, s44, 0x113000
	s_addc_u32 s47, s45, 0
	global_store_short_d16_hi v145, v154, s[46:47]
	s_add_u32 s46, s44, 0x123000
	s_addc_u32 s47, s45, 0
	global_store_short v145, v155, s[46:47]
	s_add_u32 s46, s44, 0x133000
	s_addc_u32 s47, s45, 0
	global_store_short_d16_hi v145, v155, s[46:47]
	v_pk_mul_f32 v[146:147], v[92:93], v[92:93]
	v_pk_mul_f32 v[148:149], v[94:95], v[94:95]
	v_pk_fma_f32 v[146:147], v[146:147], v[158:159], v[156:157]
	v_pk_fma_f32 v[148:149], v[148:149], v[158:159], v[156:157]
	v_pk_mul_f32 v[146:147], v[92:93], v[146:147]
	v_pk_mul_f32 v[148:149], v[94:95], v[148:149]
	v_exp_f32_e32 v146, v146
	v_exp_f32_e32 v147, v147
	v_exp_f32_e32 v148, v148
	v_exp_f32_e32 v149, v149
	v_pk_add_f32 v[146:147], v[146:147], v[160:161]
	v_pk_add_f32 v[148:149], v[148:149], v[160:161]
	v_rcp_f32_e32 v146, v146
	v_rcp_f32_e32 v147, v147
	v_rcp_f32_e32 v148, v148
	v_rcp_f32_e32 v149, v149
	v_pk_mul_f32 v[146:147], v[92:93], v[146:147]
	v_pk_mul_f32 v[148:149], v[94:95], v[148:149]
	v_cvt_pk_bf16_f32 v154, v146, v147
	v_cvt_pk_bf16_f32 v155, v148, v149
	s_add_u32 s46, s44, 0x200000
	s_addc_u32 s47, s45, 0
	global_store_short v145, v154, s[46:47]
	s_add_u32 s46, s44, 0x210000
	s_addc_u32 s47, s45, 0
	global_store_short_d16_hi v145, v154, s[46:47]
	s_add_u32 s46, s44, 0x220000
	s_addc_u32 s47, s45, 0
	global_store_short v145, v155, s[46:47]
	s_add_u32 s46, s44, 0x230000
	s_addc_u32 s47, s45, 0
	global_store_short_d16_hi v145, v155, s[46:47]
	v_pk_mul_f32 v[146:147], v[88:89], v[88:89]
	v_pk_mul_f32 v[148:149], v[90:91], v[90:91]
	v_pk_fma_f32 v[146:147], v[146:147], v[158:159], v[156:157]
	v_pk_fma_f32 v[148:149], v[148:149], v[158:159], v[156:157]
	v_pk_mul_f32 v[146:147], v[88:89], v[146:147]
	v_pk_mul_f32 v[148:149], v[90:91], v[148:149]
	v_exp_f32_e32 v146, v146
	v_exp_f32_e32 v147, v147
	v_exp_f32_e32 v148, v148
	v_exp_f32_e32 v149, v149
	v_pk_add_f32 v[146:147], v[146:147], v[160:161]
	v_pk_add_f32 v[148:149], v[148:149], v[160:161]
	v_rcp_f32_e32 v146, v146
	v_rcp_f32_e32 v147, v147
	v_rcp_f32_e32 v148, v148
	v_rcp_f32_e32 v149, v149
	v_pk_mul_f32 v[146:147], v[88:89], v[146:147]
	v_pk_mul_f32 v[148:149], v[90:91], v[148:149]
	v_cvt_pk_bf16_f32 v154, v146, v147
	v_cvt_pk_bf16_f32 v155, v148, v149
	s_add_u32 s46, s44, 0x201000
	s_addc_u32 s47, s45, 0
	global_store_short v145, v154, s[46:47]
	s_add_u32 s46, s44, 0x211000
	s_addc_u32 s47, s45, 0
	global_store_short_d16_hi v145, v154, s[46:47]
	s_add_u32 s46, s44, 0x221000
	s_addc_u32 s47, s45, 0
	global_store_short v145, v155, s[46:47]
	s_add_u32 s46, s44, 0x231000
	s_addc_u32 s47, s45, 0
	global_store_short_d16_hi v145, v155, s[46:47]
	v_pk_mul_f32 v[146:147], v[84:85], v[84:85]
	v_pk_mul_f32 v[148:149], v[86:87], v[86:87]
	v_pk_fma_f32 v[146:147], v[146:147], v[158:159], v[156:157]
	v_pk_fma_f32 v[148:149], v[148:149], v[158:159], v[156:157]
	v_pk_mul_f32 v[146:147], v[84:85], v[146:147]
	v_pk_mul_f32 v[148:149], v[86:87], v[148:149]
	v_exp_f32_e32 v146, v146
	v_exp_f32_e32 v147, v147
	v_exp_f32_e32 v148, v148
	v_exp_f32_e32 v149, v149
	v_pk_add_f32 v[146:147], v[146:147], v[160:161]
	v_pk_add_f32 v[148:149], v[148:149], v[160:161]
	v_rcp_f32_e32 v146, v146
	v_rcp_f32_e32 v147, v147
	v_rcp_f32_e32 v148, v148
	v_rcp_f32_e32 v149, v149
	v_pk_mul_f32 v[146:147], v[84:85], v[146:147]
	v_pk_mul_f32 v[148:149], v[86:87], v[148:149]
	v_cvt_pk_bf16_f32 v154, v146, v147
	v_cvt_pk_bf16_f32 v155, v148, v149
	s_add_u32 s46, s44, 0x202000
	s_addc_u32 s47, s45, 0
	global_store_short v145, v154, s[46:47]
	s_add_u32 s46, s44, 0x212000
	s_addc_u32 s47, s45, 0
	global_store_short_d16_hi v145, v154, s[46:47]
	s_add_u32 s46, s44, 0x222000
	s_addc_u32 s47, s45, 0
	global_store_short v145, v155, s[46:47]
	s_add_u32 s46, s44, 0x232000
	s_addc_u32 s47, s45, 0
	global_store_short_d16_hi v145, v155, s[46:47]
	v_pk_mul_f32 v[146:147], v[80:81], v[80:81]
	v_pk_mul_f32 v[148:149], v[82:83], v[82:83]
	v_pk_fma_f32 v[146:147], v[146:147], v[158:159], v[156:157]
	v_pk_fma_f32 v[148:149], v[148:149], v[158:159], v[156:157]
	v_pk_mul_f32 v[146:147], v[80:81], v[146:147]
	v_pk_mul_f32 v[148:149], v[82:83], v[148:149]
	v_exp_f32_e32 v146, v146
	v_exp_f32_e32 v147, v147
	v_exp_f32_e32 v148, v148
	v_exp_f32_e32 v149, v149
	v_pk_add_f32 v[146:147], v[146:147], v[160:161]
	v_pk_add_f32 v[148:149], v[148:149], v[160:161]
	v_rcp_f32_e32 v146, v146
	v_rcp_f32_e32 v147, v147
	v_rcp_f32_e32 v148, v148
	v_rcp_f32_e32 v149, v149
	v_pk_mul_f32 v[146:147], v[80:81], v[146:147]
	v_pk_mul_f32 v[148:149], v[82:83], v[148:149]
	v_cvt_pk_bf16_f32 v154, v146, v147
	v_cvt_pk_bf16_f32 v155, v148, v149
	s_add_u32 s46, s44, 0x203000
	s_addc_u32 s47, s45, 0
	global_store_short v145, v154, s[46:47]
	s_add_u32 s46, s44, 0x213000
	s_addc_u32 s47, s45, 0
	global_store_short_d16_hi v145, v154, s[46:47]
	s_add_u32 s46, s44, 0x223000
	s_addc_u32 s47, s45, 0
	global_store_short v145, v155, s[46:47]
	s_add_u32 s46, s44, 0x233000
	s_addc_u32 s47, s45, 0
	global_store_short_d16_hi v145, v155, s[46:47]
	v_pk_mul_f32 v[146:147], v[76:77], v[76:77]
	v_pk_mul_f32 v[148:149], v[78:79], v[78:79]
	v_pk_fma_f32 v[146:147], v[146:147], v[158:159], v[156:157]
	v_pk_fma_f32 v[148:149], v[148:149], v[158:159], v[156:157]
	v_pk_mul_f32 v[146:147], v[76:77], v[146:147]
	v_pk_mul_f32 v[148:149], v[78:79], v[148:149]
	v_exp_f32_e32 v146, v146
	v_exp_f32_e32 v147, v147
	v_exp_f32_e32 v148, v148
	v_exp_f32_e32 v149, v149
	v_pk_add_f32 v[146:147], v[146:147], v[160:161]
	v_pk_add_f32 v[148:149], v[148:149], v[160:161]
	v_rcp_f32_e32 v146, v146
	v_rcp_f32_e32 v147, v147
	v_rcp_f32_e32 v148, v148
	v_rcp_f32_e32 v149, v149
	v_pk_mul_f32 v[146:147], v[76:77], v[146:147]
	v_pk_mul_f32 v[148:149], v[78:79], v[148:149]
	v_cvt_pk_bf16_f32 v154, v146, v147
	v_cvt_pk_bf16_f32 v155, v148, v149
	s_add_u32 s46, s44, 0x300000
	s_addc_u32 s47, s45, 0
	global_store_short v145, v154, s[46:47]
	s_add_u32 s46, s44, 0x310000
	s_addc_u32 s47, s45, 0
	global_store_short_d16_hi v145, v154, s[46:47]
	s_add_u32 s46, s44, 0x320000
	s_addc_u32 s47, s45, 0
	global_store_short v145, v155, s[46:47]
	s_add_u32 s46, s44, 0x330000
	s_addc_u32 s47, s45, 0
	global_store_short_d16_hi v145, v155, s[46:47]
	v_pk_mul_f32 v[146:147], v[72:73], v[72:73]
	v_pk_mul_f32 v[148:149], v[74:75], v[74:75]
	v_pk_fma_f32 v[146:147], v[146:147], v[158:159], v[156:157]
	v_pk_fma_f32 v[148:149], v[148:149], v[158:159], v[156:157]
	v_pk_mul_f32 v[146:147], v[72:73], v[146:147]
	v_pk_mul_f32 v[148:149], v[74:75], v[148:149]
	v_exp_f32_e32 v146, v146
	v_exp_f32_e32 v147, v147
	v_exp_f32_e32 v148, v148
	v_exp_f32_e32 v149, v149
	v_pk_add_f32 v[146:147], v[146:147], v[160:161]
	v_pk_add_f32 v[148:149], v[148:149], v[160:161]
	v_rcp_f32_e32 v146, v146
	v_rcp_f32_e32 v147, v147
	v_rcp_f32_e32 v148, v148
	v_rcp_f32_e32 v149, v149
	v_pk_mul_f32 v[146:147], v[72:73], v[146:147]
	v_pk_mul_f32 v[148:149], v[74:75], v[148:149]
	v_cvt_pk_bf16_f32 v154, v146, v147
	v_cvt_pk_bf16_f32 v155, v148, v149
	s_add_u32 s46, s44, 0x301000
	s_addc_u32 s47, s45, 0
	global_store_short v145, v154, s[46:47]
	s_add_u32 s46, s44, 0x311000
	s_addc_u32 s47, s45, 0
	global_store_short_d16_hi v145, v154, s[46:47]
	s_add_u32 s46, s44, 0x321000
	s_addc_u32 s47, s45, 0
	global_store_short v145, v155, s[46:47]
	s_add_u32 s46, s44, 0x331000
	s_addc_u32 s47, s45, 0
	global_store_short_d16_hi v145, v155, s[46:47]
	v_pk_mul_f32 v[146:147], v[68:69], v[68:69]
	v_pk_mul_f32 v[148:149], v[70:71], v[70:71]
	v_pk_fma_f32 v[146:147], v[146:147], v[158:159], v[156:157]
	v_pk_fma_f32 v[148:149], v[148:149], v[158:159], v[156:157]
	v_pk_mul_f32 v[146:147], v[68:69], v[146:147]
	v_pk_mul_f32 v[148:149], v[70:71], v[148:149]
	v_exp_f32_e32 v146, v146
	v_exp_f32_e32 v147, v147
	v_exp_f32_e32 v148, v148
	v_exp_f32_e32 v149, v149
	v_pk_add_f32 v[146:147], v[146:147], v[160:161]
	v_pk_add_f32 v[148:149], v[148:149], v[160:161]
	v_rcp_f32_e32 v146, v146
	v_rcp_f32_e32 v147, v147
	v_rcp_f32_e32 v148, v148
	v_rcp_f32_e32 v149, v149
	v_pk_mul_f32 v[146:147], v[68:69], v[146:147]
	v_pk_mul_f32 v[148:149], v[70:71], v[148:149]
	v_cvt_pk_bf16_f32 v154, v146, v147
	v_cvt_pk_bf16_f32 v155, v148, v149
	s_add_u32 s46, s44, 0x302000
	s_addc_u32 s47, s45, 0
	global_store_short v145, v154, s[46:47]
	s_add_u32 s46, s44, 0x312000
	s_addc_u32 s47, s45, 0
	global_store_short_d16_hi v145, v154, s[46:47]
	s_add_u32 s46, s44, 0x322000
	s_addc_u32 s47, s45, 0
	global_store_short v145, v155, s[46:47]
	s_add_u32 s46, s44, 0x332000
	s_addc_u32 s47, s45, 0
	global_store_short_d16_hi v145, v155, s[46:47]
	v_pk_mul_f32 v[146:147], v[64:65], v[64:65]
	v_pk_mul_f32 v[148:149], v[66:67], v[66:67]
	v_pk_fma_f32 v[146:147], v[146:147], v[158:159], v[156:157]
	v_pk_fma_f32 v[148:149], v[148:149], v[158:159], v[156:157]
	v_pk_mul_f32 v[146:147], v[64:65], v[146:147]
	v_pk_mul_f32 v[148:149], v[66:67], v[148:149]
	v_exp_f32_e32 v146, v146
	v_exp_f32_e32 v147, v147
	v_exp_f32_e32 v148, v148
	v_exp_f32_e32 v149, v149
	v_pk_add_f32 v[146:147], v[146:147], v[160:161]
	v_pk_add_f32 v[148:149], v[148:149], v[160:161]
	v_rcp_f32_e32 v146, v146
	v_rcp_f32_e32 v147, v147
	v_rcp_f32_e32 v148, v148
	v_rcp_f32_e32 v149, v149
	v_pk_mul_f32 v[146:147], v[64:65], v[146:147]
	v_pk_mul_f32 v[148:149], v[66:67], v[148:149]
	v_cvt_pk_bf16_f32 v154, v146, v147
	v_cvt_pk_bf16_f32 v155, v148, v149
	s_add_u32 s46, s44, 0x303000
	s_addc_u32 s47, s45, 0
	global_store_short v145, v154, s[46:47]
	s_add_u32 s46, s44, 0x313000
	s_addc_u32 s47, s45, 0
	global_store_short_d16_hi v145, v154, s[46:47]
	s_add_u32 s46, s44, 0x323000
	s_addc_u32 s47, s45, 0
	global_store_short v145, v155, s[46:47]
	s_add_u32 s46, s44, 0x333000
	s_addc_u32 s47, s45, 0
	global_store_short_d16_hi v145, v155, s[46:47]
	v_pk_mul_f32 v[146:147], v[60:61], v[60:61]
	v_pk_mul_f32 v[148:149], v[62:63], v[62:63]
	v_pk_fma_f32 v[146:147], v[146:147], v[158:159], v[156:157]
	v_pk_fma_f32 v[148:149], v[148:149], v[158:159], v[156:157]
	v_pk_mul_f32 v[146:147], v[60:61], v[146:147]
	v_pk_mul_f32 v[148:149], v[62:63], v[148:149]
	v_exp_f32_e32 v146, v146
	v_exp_f32_e32 v147, v147
	v_exp_f32_e32 v148, v148
	v_exp_f32_e32 v149, v149
	v_pk_add_f32 v[146:147], v[146:147], v[160:161]
	v_pk_add_f32 v[148:149], v[148:149], v[160:161]
	v_rcp_f32_e32 v146, v146
	v_rcp_f32_e32 v147, v147
	v_rcp_f32_e32 v148, v148
	v_rcp_f32_e32 v149, v149
	v_pk_mul_f32 v[146:147], v[60:61], v[146:147]
	v_pk_mul_f32 v[148:149], v[62:63], v[148:149]
	v_cvt_pk_bf16_f32 v154, v146, v147
	v_cvt_pk_bf16_f32 v155, v148, v149
	s_add_u32 s46, s44, 0x400000
	s_addc_u32 s47, s45, 0
	global_store_short v145, v154, s[46:47]
	s_add_u32 s46, s44, 0x410000
	s_addc_u32 s47, s45, 0
	global_store_short_d16_hi v145, v154, s[46:47]
	s_add_u32 s46, s44, 0x420000
	s_addc_u32 s47, s45, 0
	global_store_short v145, v155, s[46:47]
	s_add_u32 s46, s44, 0x430000
	s_addc_u32 s47, s45, 0
	global_store_short_d16_hi v145, v155, s[46:47]
	v_pk_mul_f32 v[146:147], v[56:57], v[56:57]
	v_pk_mul_f32 v[148:149], v[58:59], v[58:59]
	v_pk_fma_f32 v[146:147], v[146:147], v[158:159], v[156:157]
	v_pk_fma_f32 v[148:149], v[148:149], v[158:159], v[156:157]
	v_pk_mul_f32 v[146:147], v[56:57], v[146:147]
	v_pk_mul_f32 v[148:149], v[58:59], v[148:149]
	v_exp_f32_e32 v146, v146
	v_exp_f32_e32 v147, v147
	v_exp_f32_e32 v148, v148
	v_exp_f32_e32 v149, v149
	v_pk_add_f32 v[146:147], v[146:147], v[160:161]
	v_pk_add_f32 v[148:149], v[148:149], v[160:161]
	v_rcp_f32_e32 v146, v146
	v_rcp_f32_e32 v147, v147
	v_rcp_f32_e32 v148, v148
	v_rcp_f32_e32 v149, v149
	v_pk_mul_f32 v[146:147], v[56:57], v[146:147]
	v_pk_mul_f32 v[148:149], v[58:59], v[148:149]
	v_cvt_pk_bf16_f32 v154, v146, v147
	v_cvt_pk_bf16_f32 v155, v148, v149
	s_add_u32 s46, s44, 0x401000
	s_addc_u32 s47, s45, 0
	global_store_short v145, v154, s[46:47]
	s_add_u32 s46, s44, 0x411000
	s_addc_u32 s47, s45, 0
	global_store_short_d16_hi v145, v154, s[46:47]
	s_add_u32 s46, s44, 0x421000
	s_addc_u32 s47, s45, 0
	global_store_short v145, v155, s[46:47]
	s_add_u32 s46, s44, 0x431000
	s_addc_u32 s47, s45, 0
	global_store_short_d16_hi v145, v155, s[46:47]
	v_pk_mul_f32 v[146:147], v[52:53], v[52:53]
	v_pk_mul_f32 v[148:149], v[54:55], v[54:55]
	v_pk_fma_f32 v[146:147], v[146:147], v[158:159], v[156:157]
	v_pk_fma_f32 v[148:149], v[148:149], v[158:159], v[156:157]
	v_pk_mul_f32 v[146:147], v[52:53], v[146:147]
	v_pk_mul_f32 v[148:149], v[54:55], v[148:149]
	v_exp_f32_e32 v146, v146
	v_exp_f32_e32 v147, v147
	v_exp_f32_e32 v148, v148
	v_exp_f32_e32 v149, v149
	v_pk_add_f32 v[146:147], v[146:147], v[160:161]
	v_pk_add_f32 v[148:149], v[148:149], v[160:161]
	v_rcp_f32_e32 v146, v146
	v_rcp_f32_e32 v147, v147
	v_rcp_f32_e32 v148, v148
	v_rcp_f32_e32 v149, v149
	v_pk_mul_f32 v[146:147], v[52:53], v[146:147]
	v_pk_mul_f32 v[148:149], v[54:55], v[148:149]
	v_cvt_pk_bf16_f32 v154, v146, v147
	v_cvt_pk_bf16_f32 v155, v148, v149
	s_add_u32 s46, s44, 0x402000
	s_addc_u32 s47, s45, 0
	global_store_short v145, v154, s[46:47]
	s_add_u32 s46, s44, 0x412000
	s_addc_u32 s47, s45, 0
	global_store_short_d16_hi v145, v154, s[46:47]
	s_add_u32 s46, s44, 0x422000
	s_addc_u32 s47, s45, 0
	global_store_short v145, v155, s[46:47]
	s_add_u32 s46, s44, 0x432000
	s_addc_u32 s47, s45, 0
	global_store_short_d16_hi v145, v155, s[46:47]
	v_pk_mul_f32 v[146:147], v[48:49], v[48:49]
	v_pk_mul_f32 v[148:149], v[50:51], v[50:51]
	v_pk_fma_f32 v[146:147], v[146:147], v[158:159], v[156:157]
	v_pk_fma_f32 v[148:149], v[148:149], v[158:159], v[156:157]
	v_pk_mul_f32 v[146:147], v[48:49], v[146:147]
	v_pk_mul_f32 v[148:149], v[50:51], v[148:149]
	v_exp_f32_e32 v146, v146
	v_exp_f32_e32 v147, v147
	v_exp_f32_e32 v148, v148
	v_exp_f32_e32 v149, v149
	v_pk_add_f32 v[146:147], v[146:147], v[160:161]
	v_pk_add_f32 v[148:149], v[148:149], v[160:161]
	v_rcp_f32_e32 v146, v146
	v_rcp_f32_e32 v147, v147
	v_rcp_f32_e32 v148, v148
	v_rcp_f32_e32 v149, v149
	v_pk_mul_f32 v[146:147], v[48:49], v[146:147]
	v_pk_mul_f32 v[148:149], v[50:51], v[148:149]
	v_cvt_pk_bf16_f32 v154, v146, v147
	v_cvt_pk_bf16_f32 v155, v148, v149
	s_add_u32 s46, s44, 0x403000
	s_addc_u32 s47, s45, 0
	global_store_short v145, v154, s[46:47]
	s_add_u32 s46, s44, 0x413000
	s_addc_u32 s47, s45, 0
	global_store_short_d16_hi v145, v154, s[46:47]
	s_add_u32 s46, s44, 0x423000
	s_addc_u32 s47, s45, 0
	global_store_short v145, v155, s[46:47]
	s_add_u32 s46, s44, 0x433000
	s_addc_u32 s47, s45, 0
	global_store_short_d16_hi v145, v155, s[46:47]
	v_pk_mul_f32 v[146:147], v[44:45], v[44:45]
	v_pk_mul_f32 v[148:149], v[46:47], v[46:47]
	v_pk_fma_f32 v[146:147], v[146:147], v[158:159], v[156:157]
	v_pk_fma_f32 v[148:149], v[148:149], v[158:159], v[156:157]
	v_pk_mul_f32 v[146:147], v[44:45], v[146:147]
	v_pk_mul_f32 v[148:149], v[46:47], v[148:149]
	v_exp_f32_e32 v146, v146
	v_exp_f32_e32 v147, v147
	v_exp_f32_e32 v148, v148
	v_exp_f32_e32 v149, v149
	v_pk_add_f32 v[146:147], v[146:147], v[160:161]
	v_pk_add_f32 v[148:149], v[148:149], v[160:161]
	v_rcp_f32_e32 v146, v146
	v_rcp_f32_e32 v147, v147
	v_rcp_f32_e32 v148, v148
	v_rcp_f32_e32 v149, v149
	v_pk_mul_f32 v[146:147], v[44:45], v[146:147]
	v_pk_mul_f32 v[148:149], v[46:47], v[148:149]
	v_cvt_pk_bf16_f32 v154, v146, v147
	v_cvt_pk_bf16_f32 v155, v148, v149
	s_add_u32 s46, s44, 0x500000
	s_addc_u32 s47, s45, 0
	global_store_short v145, v154, s[46:47]
	s_add_u32 s46, s44, 0x510000
	s_addc_u32 s47, s45, 0
	global_store_short_d16_hi v145, v154, s[46:47]
	s_add_u32 s46, s44, 0x520000
	s_addc_u32 s47, s45, 0
	global_store_short v145, v155, s[46:47]
	s_add_u32 s46, s44, 0x530000
	s_addc_u32 s47, s45, 0
	global_store_short_d16_hi v145, v155, s[46:47]
	v_pk_mul_f32 v[146:147], v[40:41], v[40:41]
	v_pk_mul_f32 v[148:149], v[42:43], v[42:43]
	v_pk_fma_f32 v[146:147], v[146:147], v[158:159], v[156:157]
	v_pk_fma_f32 v[148:149], v[148:149], v[158:159], v[156:157]
	v_pk_mul_f32 v[146:147], v[40:41], v[146:147]
	v_pk_mul_f32 v[148:149], v[42:43], v[148:149]
	v_exp_f32_e32 v146, v146
	v_exp_f32_e32 v147, v147
	v_exp_f32_e32 v148, v148
	v_exp_f32_e32 v149, v149
	v_pk_add_f32 v[146:147], v[146:147], v[160:161]
	v_pk_add_f32 v[148:149], v[148:149], v[160:161]
	v_rcp_f32_e32 v146, v146
	v_rcp_f32_e32 v147, v147
	v_rcp_f32_e32 v148, v148
	v_rcp_f32_e32 v149, v149
	v_pk_mul_f32 v[146:147], v[40:41], v[146:147]
	v_pk_mul_f32 v[148:149], v[42:43], v[148:149]
	v_cvt_pk_bf16_f32 v154, v146, v147
	v_cvt_pk_bf16_f32 v155, v148, v149
	s_add_u32 s46, s44, 0x501000
	s_addc_u32 s47, s45, 0
	global_store_short v145, v154, s[46:47]
	s_add_u32 s46, s44, 0x511000
	s_addc_u32 s47, s45, 0
	global_store_short_d16_hi v145, v154, s[46:47]
	s_add_u32 s46, s44, 0x521000
	s_addc_u32 s47, s45, 0
	global_store_short v145, v155, s[46:47]
	s_add_u32 s46, s44, 0x531000
	s_addc_u32 s47, s45, 0
	global_store_short_d16_hi v145, v155, s[46:47]
	v_pk_mul_f32 v[146:147], v[36:37], v[36:37]
	v_pk_mul_f32 v[148:149], v[38:39], v[38:39]
	v_pk_fma_f32 v[146:147], v[146:147], v[158:159], v[156:157]
	v_pk_fma_f32 v[148:149], v[148:149], v[158:159], v[156:157]
	v_pk_mul_f32 v[146:147], v[36:37], v[146:147]
	v_pk_mul_f32 v[148:149], v[38:39], v[148:149]
	v_exp_f32_e32 v146, v146
	v_exp_f32_e32 v147, v147
	v_exp_f32_e32 v148, v148
	v_exp_f32_e32 v149, v149
	v_pk_add_f32 v[146:147], v[146:147], v[160:161]
	v_pk_add_f32 v[148:149], v[148:149], v[160:161]
	v_rcp_f32_e32 v146, v146
	v_rcp_f32_e32 v147, v147
	v_rcp_f32_e32 v148, v148
	v_rcp_f32_e32 v149, v149
	v_pk_mul_f32 v[146:147], v[36:37], v[146:147]
	v_pk_mul_f32 v[148:149], v[38:39], v[148:149]
	v_cvt_pk_bf16_f32 v154, v146, v147
	v_cvt_pk_bf16_f32 v155, v148, v149
	s_add_u32 s46, s44, 0x502000
	s_addc_u32 s47, s45, 0
	global_store_short v145, v154, s[46:47]
	s_add_u32 s46, s44, 0x512000
	s_addc_u32 s47, s45, 0
	global_store_short_d16_hi v145, v154, s[46:47]
	s_add_u32 s46, s44, 0x522000
	s_addc_u32 s47, s45, 0
	global_store_short v145, v155, s[46:47]
	s_add_u32 s46, s44, 0x532000
	s_addc_u32 s47, s45, 0
	global_store_short_d16_hi v145, v155, s[46:47]
	v_pk_mul_f32 v[146:147], v[32:33], v[32:33]
	v_pk_mul_f32 v[148:149], v[34:35], v[34:35]
	v_pk_fma_f32 v[146:147], v[146:147], v[158:159], v[156:157]
	v_pk_fma_f32 v[148:149], v[148:149], v[158:159], v[156:157]
	v_pk_mul_f32 v[146:147], v[32:33], v[146:147]
	v_pk_mul_f32 v[148:149], v[34:35], v[148:149]
	v_exp_f32_e32 v146, v146
	v_exp_f32_e32 v147, v147
	v_exp_f32_e32 v148, v148
	v_exp_f32_e32 v149, v149
	v_pk_add_f32 v[146:147], v[146:147], v[160:161]
	v_pk_add_f32 v[148:149], v[148:149], v[160:161]
	v_rcp_f32_e32 v146, v146
	v_rcp_f32_e32 v147, v147
	v_rcp_f32_e32 v148, v148
	v_rcp_f32_e32 v149, v149
	v_pk_mul_f32 v[146:147], v[32:33], v[146:147]
	v_pk_mul_f32 v[148:149], v[34:35], v[148:149]
	v_cvt_pk_bf16_f32 v154, v146, v147
	v_cvt_pk_bf16_f32 v155, v148, v149
	s_add_u32 s46, s44, 0x503000
	s_addc_u32 s47, s45, 0
	global_store_short v145, v154, s[46:47]
	s_add_u32 s46, s44, 0x513000
	s_addc_u32 s47, s45, 0
	global_store_short_d16_hi v145, v154, s[46:47]
	s_add_u32 s46, s44, 0x523000
	s_addc_u32 s47, s45, 0
	global_store_short v145, v155, s[46:47]
	s_add_u32 s46, s44, 0x533000
	s_addc_u32 s47, s45, 0
	global_store_short_d16_hi v145, v155, s[46:47]
	v_pk_mul_f32 v[146:147], v[28:29], v[28:29]
	v_pk_mul_f32 v[148:149], v[30:31], v[30:31]
	v_pk_fma_f32 v[146:147], v[146:147], v[158:159], v[156:157]
	v_pk_fma_f32 v[148:149], v[148:149], v[158:159], v[156:157]
	v_pk_mul_f32 v[146:147], v[28:29], v[146:147]
	v_pk_mul_f32 v[148:149], v[30:31], v[148:149]
	v_exp_f32_e32 v146, v146
	v_exp_f32_e32 v147, v147
	v_exp_f32_e32 v148, v148
	v_exp_f32_e32 v149, v149
	v_pk_add_f32 v[146:147], v[146:147], v[160:161]
	v_pk_add_f32 v[148:149], v[148:149], v[160:161]
	v_rcp_f32_e32 v146, v146
	v_rcp_f32_e32 v147, v147
	v_rcp_f32_e32 v148, v148
	v_rcp_f32_e32 v149, v149
	v_pk_mul_f32 v[146:147], v[28:29], v[146:147]
	v_pk_mul_f32 v[148:149], v[30:31], v[148:149]
	v_cvt_pk_bf16_f32 v154, v146, v147
	v_cvt_pk_bf16_f32 v155, v148, v149
	s_add_u32 s46, s44, 0x600000
	s_addc_u32 s47, s45, 0
	global_store_short v145, v154, s[46:47]
	s_add_u32 s46, s44, 0x610000
	s_addc_u32 s47, s45, 0
	global_store_short_d16_hi v145, v154, s[46:47]
	s_add_u32 s46, s44, 0x620000
	s_addc_u32 s47, s45, 0
	global_store_short v145, v155, s[46:47]
	s_add_u32 s46, s44, 0x630000
	s_addc_u32 s47, s45, 0
	global_store_short_d16_hi v145, v155, s[46:47]
	v_pk_mul_f32 v[146:147], v[24:25], v[24:25]
	v_pk_mul_f32 v[148:149], v[26:27], v[26:27]
	v_pk_fma_f32 v[146:147], v[146:147], v[158:159], v[156:157]
	v_pk_fma_f32 v[148:149], v[148:149], v[158:159], v[156:157]
	v_pk_mul_f32 v[146:147], v[24:25], v[146:147]
	v_pk_mul_f32 v[148:149], v[26:27], v[148:149]
	v_exp_f32_e32 v146, v146
	v_exp_f32_e32 v147, v147
	v_exp_f32_e32 v148, v148
	v_exp_f32_e32 v149, v149
	v_pk_add_f32 v[146:147], v[146:147], v[160:161]
	v_pk_add_f32 v[148:149], v[148:149], v[160:161]
	v_rcp_f32_e32 v146, v146
	v_rcp_f32_e32 v147, v147
	v_rcp_f32_e32 v148, v148
	v_rcp_f32_e32 v149, v149
	v_pk_mul_f32 v[146:147], v[24:25], v[146:147]
	v_pk_mul_f32 v[148:149], v[26:27], v[148:149]
	v_cvt_pk_bf16_f32 v154, v146, v147
	v_cvt_pk_bf16_f32 v155, v148, v149
	s_add_u32 s46, s44, 0x601000
	s_addc_u32 s47, s45, 0
	global_store_short v145, v154, s[46:47]
	s_add_u32 s46, s44, 0x611000
	s_addc_u32 s47, s45, 0
	global_store_short_d16_hi v145, v154, s[46:47]
	s_add_u32 s46, s44, 0x621000
	s_addc_u32 s47, s45, 0
	global_store_short v145, v155, s[46:47]
	s_add_u32 s46, s44, 0x631000
	s_addc_u32 s47, s45, 0
	global_store_short_d16_hi v145, v155, s[46:47]
	v_pk_mul_f32 v[146:147], v[20:21], v[20:21]
	v_pk_mul_f32 v[148:149], v[22:23], v[22:23]
	v_pk_fma_f32 v[146:147], v[146:147], v[158:159], v[156:157]
	v_pk_fma_f32 v[148:149], v[148:149], v[158:159], v[156:157]
	v_pk_mul_f32 v[146:147], v[20:21], v[146:147]
	v_pk_mul_f32 v[148:149], v[22:23], v[148:149]
	v_exp_f32_e32 v146, v146
	v_exp_f32_e32 v147, v147
	v_exp_f32_e32 v148, v148
	v_exp_f32_e32 v149, v149
	v_pk_add_f32 v[146:147], v[146:147], v[160:161]
	v_pk_add_f32 v[148:149], v[148:149], v[160:161]
	v_rcp_f32_e32 v146, v146
	v_rcp_f32_e32 v147, v147
	v_rcp_f32_e32 v148, v148
	v_rcp_f32_e32 v149, v149
	v_pk_mul_f32 v[146:147], v[20:21], v[146:147]
	v_pk_mul_f32 v[148:149], v[22:23], v[148:149]
	v_cvt_pk_bf16_f32 v154, v146, v147
	v_cvt_pk_bf16_f32 v155, v148, v149
	s_add_u32 s46, s44, 0x602000
	s_addc_u32 s47, s45, 0
	global_store_short v145, v154, s[46:47]
	s_add_u32 s46, s44, 0x612000
	s_addc_u32 s47, s45, 0
	global_store_short_d16_hi v145, v154, s[46:47]
	s_add_u32 s46, s44, 0x622000
	s_addc_u32 s47, s45, 0
	global_store_short v145, v155, s[46:47]
	s_add_u32 s46, s44, 0x632000
	s_addc_u32 s47, s45, 0
	global_store_short_d16_hi v145, v155, s[46:47]
	v_pk_mul_f32 v[146:147], v[16:17], v[16:17]
	v_pk_mul_f32 v[148:149], v[18:19], v[18:19]
	v_pk_fma_f32 v[146:147], v[146:147], v[158:159], v[156:157]
	v_pk_fma_f32 v[148:149], v[148:149], v[158:159], v[156:157]
	v_pk_mul_f32 v[146:147], v[16:17], v[146:147]
	v_pk_mul_f32 v[148:149], v[18:19], v[148:149]
	v_exp_f32_e32 v146, v146
	v_exp_f32_e32 v147, v147
	v_exp_f32_e32 v148, v148
	v_exp_f32_e32 v149, v149
	v_pk_add_f32 v[146:147], v[146:147], v[160:161]
	v_pk_add_f32 v[148:149], v[148:149], v[160:161]
	v_rcp_f32_e32 v146, v146
	v_rcp_f32_e32 v147, v147
	v_rcp_f32_e32 v148, v148
	v_rcp_f32_e32 v149, v149
	v_pk_mul_f32 v[146:147], v[16:17], v[146:147]
	v_pk_mul_f32 v[148:149], v[18:19], v[148:149]
	v_cvt_pk_bf16_f32 v154, v146, v147
	v_cvt_pk_bf16_f32 v155, v148, v149
	s_add_u32 s46, s44, 0x603000
	s_addc_u32 s47, s45, 0
	global_store_short v145, v154, s[46:47]
	s_add_u32 s46, s44, 0x613000
	s_addc_u32 s47, s45, 0
	global_store_short_d16_hi v145, v154, s[46:47]
	s_add_u32 s46, s44, 0x623000
	s_addc_u32 s47, s45, 0
	global_store_short v145, v155, s[46:47]
	s_add_u32 s46, s44, 0x633000
	s_addc_u32 s47, s45, 0
	global_store_short_d16_hi v145, v155, s[46:47]
	v_pk_mul_f32 v[146:147], v[12:13], v[12:13]
	v_pk_mul_f32 v[148:149], v[14:15], v[14:15]
	v_pk_fma_f32 v[146:147], v[146:147], v[158:159], v[156:157]
	v_pk_fma_f32 v[148:149], v[148:149], v[158:159], v[156:157]
	v_pk_mul_f32 v[146:147], v[12:13], v[146:147]
	v_pk_mul_f32 v[148:149], v[14:15], v[148:149]
	v_exp_f32_e32 v146, v146
	v_exp_f32_e32 v147, v147
	v_exp_f32_e32 v148, v148
	v_exp_f32_e32 v149, v149
	v_pk_add_f32 v[146:147], v[146:147], v[160:161]
	v_pk_add_f32 v[148:149], v[148:149], v[160:161]
	v_rcp_f32_e32 v146, v146
	v_rcp_f32_e32 v147, v147
	v_rcp_f32_e32 v148, v148
	v_rcp_f32_e32 v149, v149
	v_pk_mul_f32 v[146:147], v[12:13], v[146:147]
	v_pk_mul_f32 v[148:149], v[14:15], v[148:149]
	v_cvt_pk_bf16_f32 v154, v146, v147
	v_cvt_pk_bf16_f32 v155, v148, v149
	s_add_u32 s46, s44, 0x700000
	s_addc_u32 s47, s45, 0
	global_store_short v145, v154, s[46:47]
	s_add_u32 s46, s44, 0x710000
	s_addc_u32 s47, s45, 0
	global_store_short_d16_hi v145, v154, s[46:47]
	s_add_u32 s46, s44, 0x720000
	s_addc_u32 s47, s45, 0
	global_store_short v145, v155, s[46:47]
	s_add_u32 s46, s44, 0x730000
	s_addc_u32 s47, s45, 0
	global_store_short_d16_hi v145, v155, s[46:47]
	v_pk_mul_f32 v[146:147], v[4:5], v[4:5]
	v_pk_mul_f32 v[148:149], v[6:7], v[6:7]
	v_pk_fma_f32 v[146:147], v[146:147], v[158:159], v[156:157]
	v_pk_fma_f32 v[148:149], v[148:149], v[158:159], v[156:157]
	v_pk_mul_f32 v[146:147], v[4:5], v[146:147]
	v_pk_mul_f32 v[148:149], v[6:7], v[148:149]
	v_exp_f32_e32 v146, v146
	v_exp_f32_e32 v147, v147
	v_exp_f32_e32 v148, v148
	v_exp_f32_e32 v149, v149
	v_pk_add_f32 v[146:147], v[146:147], v[160:161]
	v_pk_add_f32 v[148:149], v[148:149], v[160:161]
	v_rcp_f32_e32 v146, v146
	v_rcp_f32_e32 v147, v147
	v_rcp_f32_e32 v148, v148
	v_rcp_f32_e32 v149, v149
	v_pk_mul_f32 v[146:147], v[4:5], v[146:147]
	v_pk_mul_f32 v[148:149], v[6:7], v[148:149]
	v_cvt_pk_bf16_f32 v154, v146, v147
	v_cvt_pk_bf16_f32 v155, v148, v149
	s_add_u32 s46, s44, 0x701000
	s_addc_u32 s47, s45, 0
	global_store_short v145, v154, s[46:47]
	s_add_u32 s46, s44, 0x711000
	s_addc_u32 s47, s45, 0
	global_store_short_d16_hi v145, v154, s[46:47]
	s_add_u32 s46, s44, 0x721000
	s_addc_u32 s47, s45, 0
	global_store_short v145, v155, s[46:47]
	s_add_u32 s46, s44, 0x731000
	s_addc_u32 s47, s45, 0
	global_store_short_d16_hi v145, v155, s[46:47]
	v_pk_mul_f32 v[146:147], v[8:9], v[8:9]
	v_pk_mul_f32 v[148:149], v[10:11], v[10:11]
	v_pk_fma_f32 v[146:147], v[146:147], v[158:159], v[156:157]
	v_pk_fma_f32 v[148:149], v[148:149], v[158:159], v[156:157]
	v_pk_mul_f32 v[146:147], v[8:9], v[146:147]
	v_pk_mul_f32 v[148:149], v[10:11], v[148:149]
	v_exp_f32_e32 v146, v146
	v_exp_f32_e32 v147, v147
	v_exp_f32_e32 v148, v148
	v_exp_f32_e32 v149, v149
	v_pk_add_f32 v[146:147], v[146:147], v[160:161]
	v_pk_add_f32 v[148:149], v[148:149], v[160:161]
	v_rcp_f32_e32 v146, v146
	v_rcp_f32_e32 v147, v147
	v_rcp_f32_e32 v148, v148
	v_rcp_f32_e32 v149, v149
	v_pk_mul_f32 v[146:147], v[8:9], v[146:147]
	v_pk_mul_f32 v[148:149], v[10:11], v[148:149]
	v_cvt_pk_bf16_f32 v154, v146, v147
	v_cvt_pk_bf16_f32 v155, v148, v149
	s_add_u32 s46, s44, 0x702000
	s_addc_u32 s47, s45, 0
	global_store_short v145, v154, s[46:47]
	s_add_u32 s46, s44, 0x712000
	s_addc_u32 s47, s45, 0
	global_store_short_d16_hi v145, v154, s[46:47]
	s_add_u32 s46, s44, 0x722000
	s_addc_u32 s47, s45, 0
	global_store_short v145, v155, s[46:47]
	s_add_u32 s46, s44, 0x732000
	s_addc_u32 s47, s45, 0
	global_store_short_d16_hi v145, v155, s[46:47]
	v_pk_mul_f32 v[146:147], v[0:1], v[0:1]
	v_pk_mul_f32 v[148:149], v[2:3], v[2:3]
	v_pk_fma_f32 v[146:147], v[146:147], v[158:159], v[156:157]
	v_pk_fma_f32 v[148:149], v[148:149], v[158:159], v[156:157]
	v_pk_mul_f32 v[146:147], v[0:1], v[146:147]
	v_pk_mul_f32 v[148:149], v[2:3], v[148:149]
	v_exp_f32_e32 v146, v146
	v_exp_f32_e32 v147, v147
	v_exp_f32_e32 v148, v148
	v_exp_f32_e32 v149, v149
	v_pk_add_f32 v[146:147], v[146:147], v[160:161]
	v_pk_add_f32 v[148:149], v[148:149], v[160:161]
	v_rcp_f32_e32 v146, v146
	v_rcp_f32_e32 v147, v147
	v_rcp_f32_e32 v148, v148
	v_rcp_f32_e32 v149, v149
	v_pk_mul_f32 v[146:147], v[0:1], v[146:147]
	v_pk_mul_f32 v[148:149], v[2:3], v[148:149]
	v_cvt_pk_bf16_f32 v154, v146, v147
	v_cvt_pk_bf16_f32 v155, v148, v149
	s_add_u32 s46, s44, 0x703000
	s_addc_u32 s47, s45, 0
	global_store_short v145, v154, s[46:47]
	s_add_u32 s46, s44, 0x713000
	s_addc_u32 s47, s45, 0
	global_store_short_d16_hi v145, v154, s[46:47]
	s_add_u32 s46, s44, 0x723000
	s_addc_u32 s47, s45, 0
	global_store_short v145, v155, s[46:47]
	s_add_u32 s46, s44, 0x733000
	s_addc_u32 s47, s45, 0
	global_store_short_d16_hi v145, v155, s[46:47]
	s_add_i32 s66, s66, s82
	s_add_i32 s61, s61, s62
	s_cmpk_lt_i32 s66, 0x200
	s_cbranch_scc0 .LBB0_603
